# scan G tiles: causal mask applied under a wave-uniform branch on the diagonal tile only (no selects on off-diagonal tiles)
# speedup vs baseline: 1.0004x; 1.0004x over previous
; #define LAS __attribute__((address_space(3)))
; __device__ __forceinline__ unsigned pk2(float lo, float hi) { unsigned r; asm volatile("v_cvt_pk_bf16_f32 %0, %1, %2" : "=v"(r) : "v"(lo), "v"(hi)); return r; }
; template <bool DRY>
; __device__ __forceinline__ void ssd_chunk(SsdRegs& R, f32x4 (&st)[2], LAS unsigned char* L, bf16_t* BIG, const float* DT, float* SSQY, const SsdItem& I, int c, int tid, int lane, int wave, int li, int pi, int c16, int q4) {
;     ...
;     {
;         const int l = 16 * li + c16; const float acs_l = *(const LAS float*)(SCW + l * 4);
; #pragma unroll
;         for (int t = 0; t < 2; ++t) {
;             const int si = 2 * pi + t;
;             u32x2 w; w.x = 0u; w.y = 0u;
;             if (si <= li) {
;                 f32x4 d = (f32x4){0.f, 0.f, 0.f, 0.f};
; #pragma unroll
;                 for (int kk = 0; kk < 4; ++kk) d = __builtin_amdgcn_mfma_f32_16x16x32_bf16(SSD_FRAG(BS, PC, 16 * si, kk), cfr[kk], d, 0, 0, 0);
;                 float gv[4];
;                 const f32x4 acs_s = *(const LAS f32x4*)(SCW + (16 * si + 4 * q4) * 4), dt_s = *(const LAS f32x4*)(SCW + 256 + (16 * si + 4 * q4) * 4);
; #pragma unroll
;                 for (int e = 0; e < 4; ++e) gv[e] = d[e] * __expf(acs_l - acs_s[e]) * dt_s[e];
;                 if (si == li) {
; #pragma unroll
;                     for (int e = 0; e < 4; ++e) gv[e] = (4 * q4 + e <= c16) ? gv[e] : 0.f;
;                 }
;                 w.x = pk2(gv[0], gv[1]); w.y = pk2(gv[2], gv[3]);
;             }
;             *(LAS u32x2*)(L + GG + l * PT + (16 * si + 4 * q4) * 2) = w;
.LBB0_727:
	ds_read_b128 v[70:73], v131
	ds_read_b128 v[66:69], v131 offset:64
	ds_read_b128 v[62:65], v131 offset:128
	ds_read_b128 v[58:61], v131 offset:192
	ds_read_b32 v76, v132
	v_mov_b32_e32 v106, 0
	v_cndmask_b32_e64 v107, 0, 1, s[88:89]
	v_cmp_ne_u32_e64 s[22:23], 1, v107
	s_andn2_b64 vcc, exec, s[88:89]
	v_mov_b32_e32 v107, v106
	s_cbranch_vccnz .LBB0_729
	ds_read_b128 v[144:147], v133 offset:17408
	ds_read_b128 v[148:151], v133 offset:17472
	ds_read_b128 v[176:179], v133 offset:17536
	ds_read_b128 v[180:183], v133 offset:17600
	ds_read_b128 v[184:187], v134
	ds_read_b128 v[152:155], v134 offset:256
	s_waitcnt lgkmcnt(5)
	v_mfma_f32_16x16x32_bf16 v[144:147], v[144:147], v[70:73], 0
	s_waitcnt lgkmcnt(4)
	v_mfma_f32_16x16x32_bf16 v[144:147], v[148:151], v[66:69], v[144:147]
	s_waitcnt lgkmcnt(3)
	v_mfma_f32_16x16x32_bf16 v[144:147], v[176:179], v[62:65], v[144:147]
	s_waitcnt lgkmcnt(2)
	v_mfma_f32_16x16x32_bf16 v[144:147], v[180:183], v[58:61], v[144:147]
	s_waitcnt lgkmcnt(1)
	v_sub_f32_e32 v106, v76, v184
	v_sub_f32_e32 v107, v76, v185
	v_exp_f32_e32 v106, v106
	v_exp_f32_e32 v107, v107
	v_sub_f32_e32 v143, v76, v186
	v_pk_mul_f32 v[106:107], v[144:145], v[106:107]
	v_exp_f32_e32 v144, v143
	v_sub_f32_e32 v143, v76, v187
	v_exp_f32_e32 v145, v143
	s_waitcnt lgkmcnt(0)
	v_pk_mul_f32 v[106:107], v[152:153], v[106:107]
	v_pk_mul_f32 v[144:145], v[146:147], v[144:145]
	s_nop 0
	v_pk_mul_f32 v[144:145], v[154:155], v[144:145]
	s_cmp_eq_u64 s[4:5], 0
	s_cbranch_scc1 .Lg_nomask1
	v_cndmask_b32_e64 v106, v106, 0, s[6:7]
	v_cndmask_b32_e64 v107, 0, v107, s[8:9]
	v_cndmask_b32_e64 v144, v144, 0, s[10:11]
	v_cndmask_b32_e64 v145, v145, 0, s[12:13]
.Lg_nomask1:
	v_cvt_pk_bf16_f32 v106, v106, v107
	v_cvt_pk_bf16_f32 v107, v144, v145

; #define LAS __attribute__((address_space(3)))
; __device__ __forceinline__ unsigned pk2(float lo, float hi) { unsigned r; asm volatile("v_cvt_pk_bf16_f32 %0, %1, %2" : "=v"(r) : "v"(lo), "v"(hi)); return r; }
; template <bool DRY>
; __device__ __forceinline__ void ssd_chunk(SsdRegs& R, f32x4 (&st)[2], LAS unsigned char* L, bf16_t* BIG, const float* DT, float* SSQY, const SsdItem& I, int c, int tid, int lane, int wave, int li, int pi, int c16, int q4) {
;     ...
;         for (int t = 0; t < 2; ++t) {
;             const int si = 2 * pi + t;
;             u32x2 w; w.x = 0u; w.y = 0u;
;             if (si <= li) {
;                 f32x4 d = (f32x4){0.f, 0.f, 0.f, 0.f};
; #pragma unroll
;                 for (int kk = 0; kk < 4; ++kk) d = __builtin_amdgcn_mfma_f32_16x16x32_bf16(SSD_FRAG(BS, PC, 16 * si, kk), cfr[kk], d, 0, 0, 0);
;                 float gv[4];
;                 const f32x4 acs_s = *(const LAS f32x4*)(SCW + (16 * si + 4 * q4) * 4), dt_s = *(const LAS f32x4*)(SCW + 256 + (16 * si + 4 * q4) * 4);
; #pragma unroll
;                 for (int e = 0; e < 4; ++e) gv[e] = d[e] * __expf(acs_l - acs_s[e]) * dt_s[e];
;                 if (si == li) {
; #pragma unroll
;                     for (int e = 0; e < 4; ++e) gv[e] = (4 * q4 + e <= c16) ? gv[e] : 0.f;
;                 }
;                 w.x = pk2(gv[0], gv[1]); w.y = pk2(gv[2], gv[3]);
;             }
;             *(LAS u32x2*)(L + GG + l * PT + (16 * si + 4 * q4) * 2) = w;
.LBB0_731:
	v_mov_b32_e32 v106, 0
	s_andn2_b64 vcc, exec, s[0:1]
	v_mov_b32_e32 v107, 0
	s_cbranch_vccnz .LBB0_733
	ds_read_b128 v[146:149], v135 offset:17408
	ds_read_b128 v[150:153], v135 offset:17472
	ds_read_b128 v[176:179], v135 offset:17536
	ds_read_b128 v[180:183], v135 offset:17600
	ds_read_b128 v[184:187], v136
	ds_read_b128 v[154:157], v136 offset:256
	s_waitcnt lgkmcnt(5)
	v_mfma_f32_16x16x32_bf16 v[146:149], v[146:149], v[70:73], 0
	s_waitcnt lgkmcnt(4)
	v_mfma_f32_16x16x32_bf16 v[146:149], v[150:153], v[66:69], v[146:149]
	s_waitcnt lgkmcnt(3)
	v_mfma_f32_16x16x32_bf16 v[146:149], v[176:179], v[62:65], v[146:149]
	s_waitcnt lgkmcnt(2)
	v_mfma_f32_16x16x32_bf16 v[146:149], v[180:183], v[58:61], v[146:149]
	s_waitcnt lgkmcnt(1)
	v_sub_f32_e32 v106, v76, v184
	v_sub_f32_e32 v107, v76, v185
	v_exp_f32_e32 v106, v106
	v_exp_f32_e32 v107, v107
	v_sub_f32_e32 v143, v76, v186
	v_sub_f32_e32 v76, v76, v187
	v_pk_mul_f32 v[106:107], v[146:147], v[106:107]
	v_exp_f32_e32 v146, v143
	v_exp_f32_e32 v147, v76
	s_waitcnt lgkmcnt(0)
	v_pk_mul_f32 v[106:107], v[154:155], v[106:107]
	v_pk_mul_f32 v[146:147], v[148:149], v[146:147]
	s_nop 0
	v_pk_mul_f32 v[146:147], v[156:157], v[146:147]
	s_cmp_eq_u64 s[14:15], 0
	s_cbranch_scc1 .Lg_nomask2
	v_cndmask_b32_e64 v106, v106, 0, s[6:7]
	v_cndmask_b32_e64 v107, 0, v107, s[8:9]
	v_cndmask_b32_e64 v146, v146, 0, s[10:11]
	v_cndmask_b32_e64 v147, v147, 0, s[12:13]
.Lg_nomask2:
	v_cvt_pk_bf16_f32 v106, v106, v107
	v_cvt_pk_bf16_f32 v107, v146, v147

; #define LAS __attribute__((address_space(3)))
; __device__ __forceinline__ unsigned pk2(float lo, float hi) { unsigned r; asm volatile("v_cvt_pk_bf16_f32 %0, %1, %2" : "=v"(r) : "v"(lo), "v"(hi)); return r; }
; template <bool DRY>
; __device__ __forceinline__ void ssd_chunk(SsdRegs& R, f32x4 (&st)[2], LAS unsigned char* L, bf16_t* BIG, const float* DT, float* SSQY, const SsdItem& I, int c, int tid, int lane, int wave, int li, int pi, int c16, int q4) {
;     ...
;     bf16x8 cfr[4];
; #pragma unroll
;     for (int kk = 0; kk < 4; ++kk) cfr[kk] = SSD_FRAG(CS, PC, 16 * li, kk);
;     {
;         const int l = 16 * li + c16; const float acs_l = *(const LAS float*)(SCW + l * 4);
; #pragma unroll
;         for (int t = 0; t < 2; ++t) {
;             const int si = 2 * pi + t;
;             u32x2 w; w.x = 0u; w.y = 0u;
;             if (si <= li) {
;                 f32x4 d = (f32x4){0.f, 0.f, 0.f, 0.f};
; #pragma unroll
;                 for (int kk = 0; kk < 4; ++kk) d = __builtin_amdgcn_mfma_f32_16x16x32_bf16(SSD_FRAG(BS, PC, 16 * si, kk), cfr[kk], d, 0, 0, 0);
;                 float gv[4];
;                 const f32x4 acs_s = *(const LAS f32x4*)(SCW + (16 * si + 4 * q4) * 4), dt_s = *(const LAS f32x4*)(SCW + 256 + (16 * si + 4 * q4) * 4);
; #pragma unroll
;                 for (int e = 0; e < 4; ++e) gv[e] = d[e] * __expf(acs_l - acs_s[e]) * dt_s[e];
;                 if (si == li) {
; #pragma unroll
;                     for (int e = 0; e < 4; ++e) gv[e] = (4 * q4 + e <= c16) ? gv[e] : 0.f;
;                 }
;                 w.x = pk2(gv[0], gv[1]); w.y = pk2(gv[2], gv[3]);
;             }
;             *(LAS u32x2*)(L + GG + l * PT + (16 * si + 4 * q4) * 2) = w;
.LBB0_742:
	ds_read_b128 v[70:73], v131
	ds_read_b128 v[66:69], v131 offset:64
	ds_read_b128 v[62:65], v131 offset:128
	ds_read_b128 v[58:61], v131 offset:192
	ds_read_b32 v76, v132
	v_mov_b32_e32 v100, 0
	s_and_b64 vcc, exec, s[22:23]
	v_mov_b32_e32 v101, v100
	s_cbranch_vccnz .LBB0_748
	ds_read_b128 v[100:103], v133 offset:17408
	ds_read_b128 v[148:151], v133 offset:17472
	ds_read_b128 v[176:179], v133 offset:17536
	ds_read_b128 v[180:183], v133 offset:17600
	ds_read_b128 v[184:187], v134
	ds_read_b128 v[152:155], v134 offset:256
	s_waitcnt lgkmcnt(5)
	v_mfma_f32_16x16x32_bf16 v[100:103], v[100:103], v[70:73], 0
	s_waitcnt lgkmcnt(4)
	v_mfma_f32_16x16x32_bf16 v[100:103], v[148:151], v[66:69], v[100:103]
	s_waitcnt lgkmcnt(3)
	v_mfma_f32_16x16x32_bf16 v[100:103], v[176:179], v[62:65], v[100:103]
	s_waitcnt lgkmcnt(2)
	v_mfma_f32_16x16x32_bf16 v[100:103], v[180:183], v[58:61], v[100:103]
	s_nop 1
	s_waitcnt lgkmcnt(1)
	v_sub_f32_e32 v104, v76, v184
	v_sub_f32_e32 v105, v76, v185
	v_exp_f32_e32 v104, v104
	v_exp_f32_e32 v105, v105
	s_nop 0
	v_pk_mul_f32 v[100:101], v[100:101], v[104:105]
	v_sub_f32_e32 v104, v76, v186
	v_sub_f32_e32 v105, v76, v187
	v_exp_f32_e32 v104, v104
	v_exp_f32_e32 v105, v105
	s_waitcnt lgkmcnt(0)
	v_pk_mul_f32 v[100:101], v[152:153], v[100:101]
	v_pk_mul_f32 v[102:103], v[102:103], v[104:105]
	s_nop 0
	v_pk_mul_f32 v[102:103], v[154:155], v[102:103]
	s_cmp_eq_u64 s[4:5], 0
	s_cbranch_scc1 .Lg_nomask3
	v_cndmask_b32_e64 v100, v100, 0, s[6:7]
	v_cndmask_b32_e64 v101, 0, v101, s[8:9]
	v_cndmask_b32_e64 v102, v102, 0, s[10:11]
	v_cndmask_b32_e64 v103, v103, 0, s[12:13]
.Lg_nomask3:
	v_cvt_pk_bf16_f32 v100, v100, v101
	v_cvt_pk_bf16_f32 v101, v102, v103
	s_and_b64 vcc, exec, s[24:25]
	s_mov_b64 s[0:1], -1
	ds_write_b64 v144, v[100:101]
	s_cbranch_vccz .LBB0_749

; #define LAS __attribute__((address_space(3)))
; __device__ __forceinline__ unsigned pk2(float lo, float hi) { unsigned r; asm volatile("v_cvt_pk_bf16_f32 %0, %1, %2" : "=v"(r) : "v"(lo), "v"(hi)); return r; }
; template <bool DRY>
; __device__ __forceinline__ void ssd_chunk(SsdRegs& R, f32x4 (&st)[2], LAS unsigned char* L, bf16_t* BIG, const float* DT, float* SSQY, const SsdItem& I, int c, int tid, int lane, int wave, int li, int pi, int c16, int q4) {
;     ...
;         for (int t = 0; t < 2; ++t) {
;             const int si = 2 * pi + t;
;             u32x2 w; w.x = 0u; w.y = 0u;
;             if (si <= li) {
;                 f32x4 d = (f32x4){0.f, 0.f, 0.f, 0.f};
; #pragma unroll
;                 for (int kk = 0; kk < 4; ++kk) d = __builtin_amdgcn_mfma_f32_16x16x32_bf16(SSD_FRAG(BS, PC, 16 * si, kk), cfr[kk], d, 0, 0, 0);
;                 float gv[4];
;                 const f32x4 acs_s = *(const LAS f32x4*)(SCW + (16 * si + 4 * q4) * 4), dt_s = *(const LAS f32x4*)(SCW + 256 + (16 * si + 4 * q4) * 4);
; #pragma unroll
;                 for (int e = 0; e < 4; ++e) gv[e] = d[e] * __expf(acs_l - acs_s[e]) * dt_s[e];
;                 if (si == li) {
; #pragma unroll
;                     for (int e = 0; e < 4; ++e) gv[e] = (4 * q4 + e <= c16) ? gv[e] : 0.f;
;                 }
;                 w.x = pk2(gv[0], gv[1]); w.y = pk2(gv[2], gv[3]);
;             }
;             *(LAS u32x2*)(L + GG + l * PT + (16 * si + 4 * q4) * 2) = w;
.LBB0_745:
	ds_read_b128 v[100:103], v135 offset:17408
	ds_read_b128 v[148:151], v135 offset:17472
	ds_read_b128 v[176:179], v135 offset:17536
	ds_read_b128 v[180:183], v135 offset:17600
	ds_read_b128 v[184:187], v136
	ds_read_b128 v[152:155], v136 offset:256
	s_waitcnt lgkmcnt(5)
	v_mfma_f32_16x16x32_bf16 v[100:103], v[100:103], v[70:73], 0
	s_waitcnt lgkmcnt(4)
	v_mfma_f32_16x16x32_bf16 v[100:103], v[148:151], v[66:69], v[100:103]
	s_waitcnt lgkmcnt(3)
	v_mfma_f32_16x16x32_bf16 v[100:103], v[176:179], v[62:65], v[100:103]
	s_waitcnt lgkmcnt(2)
	v_mfma_f32_16x16x32_bf16 v[100:103], v[180:183], v[58:61], v[100:103]
	s_nop 1
	s_waitcnt lgkmcnt(1)
	v_sub_f32_e32 v104, v76, v184
	v_sub_f32_e32 v105, v76, v185
	v_exp_f32_e32 v104, v104
	v_exp_f32_e32 v105, v105
	s_nop 0
	v_pk_mul_f32 v[100:101], v[100:101], v[104:105]
	v_sub_f32_e32 v104, v76, v186
	v_sub_f32_e32 v76, v76, v187
	v_exp_f32_e32 v104, v104
	v_exp_f32_e32 v105, v76
	s_waitcnt lgkmcnt(0)
	v_pk_mul_f32 v[100:101], v[152:153], v[100:101]
	v_pk_mul_f32 v[102:103], v[102:103], v[104:105]
	s_nop 0
	v_pk_mul_f32 v[102:103], v[154:155], v[102:103]
	s_cmp_eq_u64 s[14:15], 0
	s_cbranch_scc1 .Lg_nomask4
	v_cndmask_b32_e64 v100, v100, 0, s[6:7]
	v_cndmask_b32_e64 v101, 0, v101, s[8:9]
	v_cndmask_b32_e64 v102, v102, 0, s[10:11]
	v_cndmask_b32_e64 v103, v103, 0, s[12:13]
.Lg_nomask4:
	v_cvt_pk_bf16_f32 v100, v100, v101
	v_cvt_pk_bf16_f32 v101, v102, v103
